# b11 + balanced assignment of query blocks to workgroups in attention (max 98 instead of 101 key-block steps per 4 items)
# speedup vs baseline: 1.0012x; 1.0012x over previous
.LBB0_1266:
	s_cmp_lt_i32 s72, 1
	s_cbranch_scc1 .LBB0_1477
	s_ashr_i32 s4, s33, 6
	s_bfe_u32 s3, s33, 0x30003
	s_add_u32 s56, s44, 0x17800000
	s_addc_u32 s57, s45, 0
	s_add_u32 s76, s44, 0x34800000
	s_addc_u32 s77, s45, 0
	s_add_u32 s73, s44, 0x35c40000
	v_writelane_b32 v235, s8, 49
	s_addc_u32 s19, s45, 0
	s_lshl_b32 s1, s33, 4
	v_writelane_b32 v235, s9, 50
	s_and_b32 s1, s1, 0x70
	v_writelane_b32 v235, s4, 51
	s_add_i32 s1, s1, s4
	v_writelane_b32 v235, s1, 52
	s_mul_i32 s100, s3, 5
	s_mov_b32 s98, 0x50748144
	s_mov_b32 s99, 0x71
	s_lshr_b64 s[0:1], s[98:99], s100
	s_and_b32 s1, s0, 31
	v_writelane_b32 v235, s1, 53
	s_mov_b32 s98, 0x39387b35
	s_mov_b32 s99, 0xde
	s_lshr_b64 s[0:1], s[98:99], s100
	s_and_b32 s1, s0, 31
	v_writelane_b32 v235, s1, 54
	s_mov_b32 s98, 0xc4c5982d
	s_mov_b32 s99, 0x1b
	s_lshr_b64 s[0:1], s[98:99], s100
	s_and_b32 s1, s0, 31
	v_writelane_b32 v235, s1, 55
	s_mov_b32 s98, 0x754b7fb7
	s_mov_b32 s99, 0x94
	s_lshr_b64 s[0:1], s[98:99], s100
	s_and_b32 s1, s0, 31
	v_writelane_b32 v235, s1, 56
	s_ashr_i32 s0, s6, 6
	v_and_b32_e32 v1, 63, v107
	s_lshl_b32 s1, s0, 5
	s_lshl_b32 s0, s0, 13
	s_add_i32 s0, s0, 0
	v_lshlrev_b32_e32 v8, 2, v1
	s_ashr_i32 s21, s6, 7
	v_bfe_u32 v3, v107, 5, 1
	s_add_i32 s6, s0, 0x12c00
	v_xor_b32_e32 v155, 0x80, v8
	v_or_b32_e32 v8, 32, v1
	s_mov_b32 s0, 0xffffffc
	s_and_b32 s60, s1, 32
	v_mul_u32_u24_e32 v158, 0x90, v8
	v_mul_lo_u32 v159, v3, s0
	v_lshlrev_b32_e32 v8, 1, v107
	s_lshl_b32 s0, s21, 6
	v_and_b32_e32 v152, 31, v107
	v_lshlrev_b32_e32 v153, 2, v3
	v_and_b32_e32 v11, 32, v8
	v_lshlrev_b32_e32 v8, 3, v107
	s_or_b32 s0, s60, s0
	v_add_u32_e32 v0, 0, v153
	s_movk_i32 s1, 0x540
	v_and_b32_e32 v13, 24, v8
	v_or_b32_e32 v8, s0, v152
	s_movk_i32 s7, 0x84
	v_cmp_gt_i32_e64 s[22:23], s1, v107
	v_mad_u64_u32 v[110:111], s[0:1], v8, s7, v[0:1]
	v_cmp_gt_i32_e64 s[0:1], 64, v107
	s_add_i32 s2, 0, 0x11400
	v_ashrrev_i32_e32 v108, 3, v107
	v_writelane_b32 v235, s0, 57
	s_movk_i32 s68, 0xc00
	v_lshlrev_b32_e32 v14, 2, v107
	v_writelane_b32 v235, s1, 58
	s_lshl_b32 s0, s60, 2
	s_add_i32 s0, s0, s2
	v_lshl_add_u32 v194, v152, 2, s0
	v_mad_i64_i32 v[112:113], s[0:1], v108, s68, 0
	v_mad_u32_u24 v156, v3, 12, v0
	v_add_u32_e32 v111, s2, v14
	v_mul_lo_u32 v0, v108, s7
	v_lshl_add_u32 v193, v108, 2, s2
	v_ashrrev_i32_e32 v109, 31, v108
	s_add_i32 s2, 0, 0x11500
	s_lshl_b32 s0, s21, 2
	v_and_b32_e32 v5, 7, v107
	s_movk_i32 s3, 0x90
	v_add_u32_e32 v192, 0, v0
	s_mul_i32 s69, s21, 0x540
	s_add_i32 s69, s69, s2
	v_mov_b32_e32 v0, s6
	v_lshlrev_b64 v[114:115], 8, v[108:109]
	s_mov_b64 s[0:1], 0x4000
	v_lshlrev_b32_e32 v9, 4, v1
	v_cmp_gt_u32_e64 s[4:5], 32, v1
	v_mad_u32_u24 v15, v152, s3, v0
	v_lshl_add_u64 v[0:1], v[114:115], 0, s[0:1]
	v_cmp_lt_u32_e64 s[0:1], 4, v5
	v_lshlrev_b32_e32 v191, 2, v5
	v_or_b32_e32 v198, 2, v191
	v_writelane_b32 v235, s0, 59
	v_or_b32_e32 v199, 3, v191
	v_lshlrev_b32_e32 v2, 3, v3
	v_writelane_b32 v235, s1, 60
	v_cmp_lt_u32_e64 s[0:1], 5, v5
	v_mul_lo_u32 v6, v108, s3
	v_lshlrev_b32_e32 v7, 4, v5
	v_writelane_b32 v235, s0, 61
	v_lshrrev_b32_e32 v3, 2, v107
	v_bfe_u32 v8, v107, 3, 3
	v_writelane_b32 v235, s1, 62
	v_cmp_eq_u32_e64 s[0:1], 7, v5
	v_and_or_b32 v3, v3, 3, v153
	v_add3_u32 v195, 0, v6, v7
	v_writelane_b32 v235, s0, 33
	v_add_u32_e32 v16, s6, v7
	v_add_u32_e32 v109, v192, v7
	v_writelane_b32 v235, s1, 34
	v_cmp_lt_u32_e64 s[0:1], 5, v198
	v_lshlrev_b32_e32 v6, 10, v8
	v_or_b32_e32 v7, 8, v8
	v_writelane_b32 v235, s0, 63
	s_mov_b32 s41, 0
	v_lshlrev_b32_e32 v4, 3, v5
	v_writelane_b32 v234, s1, 0
	v_cmp_lt_u32_e64 s[0:1], 9, v198
	v_cmp_eq_u32_e64 s[78:79], 0, v5
	v_mul_u32_u24_e32 v17, 0x90, v8
	v_writelane_b32 v234, s0, 1
	v_mul_u32_u24_e32 v18, 0x90, v7
	v_lshlrev_b32_e32 v8, 10, v7
	v_writelane_b32 v234, s1, 2
	v_cmp_lt_u32_e64 s[0:1], 13, v198
	v_or_b32_e32 v10, 0x4000, v6
	v_or_b32_e32 v12, 0x6000, v6
	v_writelane_b32 v234, s0, 3
	v_mad_u32_u24 v3, v3, s3, 0
	v_or_b32_e32 v154, s60, v152
	v_writelane_b32 v234, s1, 4
	v_cmp_lt_u32_e64 s[0:1], 17, v198
	v_mov_b32_e32 v32, 0
	v_mul_u32_u24_e32 v157, 0x90, v152
	v_writelane_b32 v234, s0, 5
	v_add_u32_e32 v160, 0xffffffe, v159
	v_add_u32_e32 v161, 0xffffffd, v159
	v_writelane_b32 v234, s1, 6
	v_cmp_lt_u32_e64 s[0:1], 21, v198
	v_add_u32_e32 v162, 0xffffff8, v159
	v_add_u32_e32 v163, 0xffffff7, v159
	v_writelane_b32 v234, s0, 7
	v_add_u32_e32 v164, 0xffffff6, v159
	v_add_u32_e32 v165, 0xffffff5, v159
	v_writelane_b32 v234, s1, 8
	v_cmp_lt_u32_e64 s[0:1], 25, v198
	v_add_u32_e32 v166, 0xffffff0, v159
	v_add_u32_e32 v167, 0xfffffef, v159
	v_writelane_b32 v234, s0, 9
	v_add_u32_e32 v168, 0xfffffee, v159
	v_add_u32_e32 v169, 0xfffffed, v159
	v_writelane_b32 v234, s1, 10
	v_cmp_lt_u32_e64 s[0:1], 4, v199
	v_add_u32_e32 v170, 0xfffffe8, v159
	v_add_u32_e32 v171, 0xfffffe7, v159
	v_writelane_b32 v234, s0, 11
	v_add_u32_e32 v172, 0xfffffe6, v159
	v_add_u32_e32 v173, 0xfffffe5, v159
	v_writelane_b32 v234, s1, 12
	v_cmp_lt_u32_e64 s[0:1], 5, v199
	v_add_u32_e32 v174, 0xfffffe0, v159
	v_add_u32_e32 v175, 0xfffffdf, v159
	v_writelane_b32 v234, s0, 13
	v_add_u32_e32 v176, 0xfffffde, v159
	v_add_u32_e32 v177, 0xfffffdd, v159
	v_writelane_b32 v234, s1, 14
	v_cmp_lt_u32_e64 s[0:1], 6, v199
	v_add_u32_e32 v178, 0xfffffd8, v159
	v_add_u32_e32 v179, 0xfffffd7, v159
	v_writelane_b32 v234, s0, 15
	v_add_u32_e32 v180, 0xfffffd6, v159
	v_add_u32_e32 v181, 0xfffffd5, v159
	v_writelane_b32 v234, s1, 16
	v_cmp_lt_u32_e64 s[0:1], 8, v199
	v_add_u32_e32 v182, 0xfffffd0, v159
	v_add_u32_e32 v183, 0xfffffcf, v159
	v_writelane_b32 v234, s0, 17
	v_add_u32_e32 v184, 0xfffffce, v159
	v_add_u32_e32 v185, 0xfffffcd, v159
	v_writelane_b32 v234, s1, 18
	v_cmp_lt_u32_e64 s[0:1], 9, v199
	v_add_u32_e32 v186, 0xfffffc8, v159
	v_add_u32_e32 v187, 0xfffffc7, v159
	v_writelane_b32 v234, s0, 19
	v_add_u32_e32 v189, 0xfffffc6, v159
	v_add_u32_e32 v190, 0xfffffc5, v159
	v_writelane_b32 v234, s1, 20
	v_cmp_lt_u32_e64 s[0:1], 10, v199
	s_mov_b32 s61, s41
	v_and_b32_e32 v196, 3, v107
	v_writelane_b32 v234, s0, 21
	v_or_b32_e32 v197, 1, v191
	v_cmp_ne_u32_e64 s[10:11], 0, v5
	v_writelane_b32 v234, s1, 22
	v_cmp_lt_u32_e64 s[0:1], 12, v199
	v_cmp_lt_u32_e64 s[12:13], 1, v5
	v_cmp_lt_u32_e64 s[14:15], 2, v5
	v_writelane_b32 v234, s0, 23
	v_cmp_lt_u32_e64 s[16:17], 3, v5
	v_lshlrev_b32_e64 v200, v191, 1
	v_writelane_b32 v234, s1, 24
	v_cmp_lt_u32_e64 s[0:1], 13, v199
	v_lshlrev_b32_e64 v201, v191, 2
	v_lshlrev_b32_e64 v202, v191, 4
	v_writelane_b32 v234, s0, 25
	v_lshlrev_b32_e64 v203, v191, 8
	v_add3_u32 v204, v3, v11, v13
	v_writelane_b32 v234, s1, 26
	v_cmp_lt_u32_e64 s[0:1], 14, v199
	v_and_b32_e32 v205, -4, v107
	v_mul_u32_u24_e32 v252, 0x540, v196
	v_add3_u32 v205, v205, v252, s2
	v_lshlrev_b32_e32 v116, 1, v2
	v_writelane_b32 v234, s0, 27
	s_movk_i32 s20, 0xc0
	s_add_i32 s71, 0, 0x12a00
	v_writelane_b32 v234, s1, 28
	v_cmp_lt_u32_e64 s[0:1], 16, v199
	v_lshlrev_b64 v[118:119], 1, v[0:1]
	s_mov_b32 s70, 0xff800000
	v_writelane_b32 v234, s0, 29
	v_lshlrev_b32_e32 v120, 1, v4
	s_movk_i32 s67, 0x1ff
	v_writelane_b32 v234, s1, 30
	v_cmp_lt_u32_e64 s[0:1], 17, v199
	v_add_u32_e32 v206, v15, v2
	v_add_u32_e32 v207, v16, v17
	v_writelane_b32 v234, s0, 31
	v_lshlrev_b32_e32 v122, 1, v6
	v_add_u32_e32 v208, v16, v18
	v_writelane_b32 v234, s1, 32
	v_cmp_lt_u32_e64 s[0:1], 18, v199
	v_lshlrev_b32_e32 v124, 1, v8
	v_lshlrev_b32_e32 v126, 1, v10
	v_writelane_b32 v234, s0, 33
	v_lshlrev_b32_e32 v128, 1, v12
	v_mov_b32_e32 v209, 0x7f
	v_writelane_b32 v234, s1, 34
	v_cmp_lt_u32_e64 s[0:1], 20, v199
	v_add_u32_e32 v210, s6, v9
	v_mov_b32_e32 v211, 0xff800000
	v_writelane_b32 v234, s0, 35
	v_mov_b32_e32 v212, 0x7f800000
	s_mov_b32 s38, 0
	v_writelane_b32 v234, s1, 36
	v_cmp_lt_u32_e64 s[0:1], 21, v199
	s_mov_b32 s44, 0x3fb8aa3b
	s_nop 0
	v_writelane_b32 v234, s0, 37
	s_nop 1
	v_writelane_b32 v234, s1, 38
	v_cmp_lt_u32_e64 s[0:1], 22, v199
	s_nop 1
	v_writelane_b32 v234, s0, 39
	s_nop 1
	v_writelane_b32 v234, s1, 40
	v_cmp_lt_u32_e64 s[0:1], 24, v199
	s_nop 1
	v_writelane_b32 v234, s0, 41
	s_nop 1
	v_writelane_b32 v234, s1, 42
	v_cmp_lt_u32_e64 s[0:1], 25, v199
	s_nop 1
	v_writelane_b32 v234, s0, 43
	s_nop 1
	v_writelane_b32 v234, s1, 44
	v_cmp_lt_u32_e64 s[0:1], 26, v199
	s_nop 1
	v_writelane_b32 v234, s0, 45
	s_nop 1
	v_writelane_b32 v234, s1, 46
	v_cmp_lt_u32_e64 s[0:1], 28, v199
	s_nop 1
	v_writelane_b32 v234, s0, 47
	s_nop 1
	v_writelane_b32 v234, s1, 48
	v_cmp_lt_u32_e64 s[0:1], 29, v199
	s_nop 1
	v_writelane_b32 v234, s0, 49
	s_nop 1
	v_writelane_b32 v234, s1, 50
	v_writelane_b32 v234, s96, 51
	s_nop 1
	v_writelane_b32 v234, s97, 52
	v_writelane_b32 v234, s78, 53
	s_nop 1
	v_writelane_b32 v234, s79, 54
	s_branch .LBB0_1270
